# R3 third state stage restructured like the first (fragment reads four ahead through dead registers)
# speedup vs baseline: 1.0013x; 1.0007x over previous
.LBB0_1090:
	s_nop 3
	ds_read_b128 v[180:183], v213
	ds_read_b128 v[236:239], v213 offset:34816
	ds_read_b128 v[240:243], v213 offset:64
	ds_read_b128 v[244:247], v213 offset:34880
	s_waitcnt lgkmcnt(3)
	v_mfma_f32_16x16x32_bf16 v[64:67], v[180:183], v[0:3], 0
	ds_read_b128 v[250:253], v213 offset:128
	s_lshl_b32 s18, s95, 9
	s_waitcnt lgkmcnt(3)
	v_mfma_f32_16x16x32_bf16 v[68:71], v[236:239], v[0:3], 0
	ds_read_b128 v[180:183], v213 offset:34944
	s_or_b32 s54, s54, s18
	s_waitcnt lgkmcnt(3)
	v_mfma_f32_16x16x32_bf16 v[64:67], v[240:243], v[4:7], v[64:67]
	ds_read_b128 v[236:239], v213 offset:192
	s_lshl_b32 s42, s93, 8
	s_waitcnt lgkmcnt(3)
	v_mfma_f32_16x16x32_bf16 v[68:71], v[244:247], v[4:7], v[68:71]
	ds_read_b128 v[240:243], v213 offset:35008
	s_lshl_b64 s[18:19], s[54:55], 11
	s_waitcnt lgkmcnt(3)
	v_mfma_f32_16x16x32_bf16 v[64:67], v[250:253], v[8:11], v[64:67]
	ds_read_b128 v[244:247], v213 offset:256
	s_add_u32 s34, s38, s18
	s_waitcnt lgkmcnt(3)
	v_mfma_f32_16x16x32_bf16 v[68:71], v[180:183], v[8:11], v[68:71]
	ds_read_b128 v[250:253], v213 offset:35072
	s_addc_u32 s35, s39, s19
	s_waitcnt lgkmcnt(3)
	v_mfma_f32_16x16x32_bf16 v[64:67], v[236:239], v[12:15], v[64:67]
	ds_read_b128 v[180:183], v213 offset:320
	s_lshl_b32 s54, s94, 9
	s_waitcnt lgkmcnt(3)
	v_mfma_f32_16x16x32_bf16 v[68:71], v[240:243], v[12:15], v[68:71]
	ds_read_b128 v[236:239], v213 offset:35136
	s_and_b32 s58, s54, 0x600
	s_waitcnt lgkmcnt(3)
	v_mfma_f32_16x16x32_bf16 v[64:67], v[244:247], v[16:19], v[64:67]
	ds_read_b128 v[240:243], v213 offset:384
	s_add_u32 s54, s34, s58
	s_waitcnt lgkmcnt(3)
	v_mfma_f32_16x16x32_bf16 v[68:71], v[250:253], v[16:19], v[68:71]
	ds_read_b128 v[244:247], v213 offset:35200
	s_addc_u32 s55, s35, 0
	s_waitcnt lgkmcnt(3)
	v_mfma_f32_16x16x32_bf16 v[64:67], v[180:183], v[20:23], v[64:67]
	ds_read_b128 v[250:253], v213 offset:448
	s_add_u32 s18, s56, s18
	s_waitcnt lgkmcnt(3)
	v_mfma_f32_16x16x32_bf16 v[68:71], v[236:239], v[20:23], v[68:71]
	ds_read_b128 v[180:183], v213 offset:35264
	s_addc_u32 s19, s57, s19
	s_waitcnt lgkmcnt(3)
	v_mfma_f32_16x16x32_bf16 v[64:67], v[240:243], v[24:27], v[64:67]
	ds_read_b128 v[236:239], v213 offset:8704
	s_add_u32 s58, s18, s58
	s_waitcnt lgkmcnt(3)
	v_mfma_f32_16x16x32_bf16 v[68:71], v[244:247], v[24:27], v[68:71]
	ds_read_b128 v[240:243], v213 offset:43520
	s_addc_u32 s59, s19, 0
	s_waitcnt lgkmcnt(3)
	v_mfma_f32_16x16x32_bf16 v[64:67], v[250:253], v[28:31], v[64:67]
	ds_read_b128 v[244:247], v213 offset:8768
	v_lshl_add_u64 v[76:77], s[54:55], 0, v[148:149]
	s_waitcnt lgkmcnt(3)
	v_mfma_f32_16x16x32_bf16 v[68:71], v[180:183], v[28:31], v[68:71]
	ds_read_b128 v[250:253], v213 offset:43584
	s_mov_b32 m0, s21
	s_waitcnt lgkmcnt(3)
	v_mfma_f32_16x16x32_bf16 v[72:75], v[236:239], v[0:3], 0
	ds_read_b128 v[180:183], v213 offset:8832
	s_and_b64 vcc, exec, s[4:5]
	s_waitcnt lgkmcnt(3)
	v_mfma_f32_16x16x32_bf16 v[92:95], v[240:243], v[0:3], 0
	ds_read_b128 v[236:239], v213 offset:43648
	s_waitcnt lgkmcnt(3)
	v_mfma_f32_16x16x32_bf16 v[72:75], v[244:247], v[4:7], v[72:75]
	ds_read_b128 v[240:243], v213 offset:8896
	s_waitcnt lgkmcnt(3)
	v_mfma_f32_16x16x32_bf16 v[92:95], v[250:253], v[4:7], v[92:95]
	ds_read_b128 v[244:247], v213 offset:43712
	s_waitcnt lgkmcnt(3)
	v_mfma_f32_16x16x32_bf16 v[72:75], v[180:183], v[8:11], v[72:75]
	ds_read_b128 v[250:253], v213 offset:8960
	s_waitcnt lgkmcnt(3)
	v_mfma_f32_16x16x32_bf16 v[92:95], v[236:239], v[8:11], v[92:95]
	ds_read_b128 v[180:183], v213 offset:43776
	s_waitcnt lgkmcnt(3)
	v_mfma_f32_16x16x32_bf16 v[72:75], v[240:243], v[12:15], v[72:75]
	ds_read_b128 v[236:239], v213 offset:9024
	s_waitcnt lgkmcnt(3)
	v_mfma_f32_16x16x32_bf16 v[92:95], v[244:247], v[12:15], v[92:95]
	ds_read_b128 v[240:243], v213 offset:43840
	s_waitcnt lgkmcnt(3)
	v_mfma_f32_16x16x32_bf16 v[72:75], v[250:253], v[16:19], v[72:75]
	ds_read_b128 v[244:247], v213 offset:9088
	s_waitcnt lgkmcnt(3)
	v_mfma_f32_16x16x32_bf16 v[92:95], v[180:183], v[16:19], v[92:95]
	ds_read_b128 v[250:253], v213 offset:43904
	s_waitcnt lgkmcnt(3)
	v_mfma_f32_16x16x32_bf16 v[72:75], v[236:239], v[20:23], v[72:75]
	ds_read_b128 v[180:183], v213 offset:9152
	s_waitcnt lgkmcnt(3)
	v_mfma_f32_16x16x32_bf16 v[92:95], v[240:243], v[20:23], v[92:95]
	ds_read_b128 v[236:239], v213 offset:43968
	s_waitcnt lgkmcnt(3)
	v_mfma_f32_16x16x32_bf16 v[72:75], v[244:247], v[24:27], v[72:75]
	ds_read_b128 v[240:243], v213 offset:17408
	s_waitcnt lgkmcnt(3)
	v_mfma_f32_16x16x32_bf16 v[92:95], v[250:253], v[24:27], v[92:95]
	ds_read_b128 v[244:247], v213 offset:52224
	s_waitcnt lgkmcnt(3)
	v_mfma_f32_16x16x32_bf16 v[72:75], v[180:183], v[28:31], v[72:75]
	ds_read_b128 v[250:253], v213 offset:17472
	s_waitcnt lgkmcnt(3)
	v_mfma_f32_16x16x32_bf16 v[92:95], v[236:239], v[28:31], v[92:95]
	ds_read_b128 v[180:183], v213 offset:52288
	s_waitcnt lgkmcnt(3)
	v_mfma_f32_16x16x32_bf16 v[116:119], v[240:243], v[0:3], 0
	ds_read_b128 v[236:239], v213 offset:17536
	s_waitcnt lgkmcnt(3)
	v_mfma_f32_16x16x32_bf16 v[120:123], v[244:247], v[0:3], 0
	ds_read_b128 v[240:243], v213 offset:52352
	s_waitcnt lgkmcnt(3)
	v_mfma_f32_16x16x32_bf16 v[116:119], v[250:253], v[4:7], v[116:119]
	ds_read_b128 v[244:247], v213 offset:17600
	s_waitcnt lgkmcnt(3)
	v_mfma_f32_16x16x32_bf16 v[120:123], v[180:183], v[4:7], v[120:123]
	ds_read_b128 v[250:253], v213 offset:52416
	s_waitcnt lgkmcnt(3)
	v_mfma_f32_16x16x32_bf16 v[116:119], v[236:239], v[8:11], v[116:119]
	ds_read_b128 v[180:183], v213 offset:17664
	s_waitcnt lgkmcnt(3)
	v_mfma_f32_16x16x32_bf16 v[120:123], v[240:243], v[8:11], v[120:123]
	ds_read_b128 v[236:239], v213 offset:52480
	s_waitcnt lgkmcnt(3)
	v_mfma_f32_16x16x32_bf16 v[116:119], v[244:247], v[12:15], v[116:119]
	ds_read_b128 v[240:243], v213 offset:17728
	s_waitcnt lgkmcnt(3)
	v_mfma_f32_16x16x32_bf16 v[120:123], v[250:253], v[12:15], v[120:123]
	ds_read_b128 v[244:247], v213 offset:52544
	s_waitcnt lgkmcnt(3)
	v_mfma_f32_16x16x32_bf16 v[116:119], v[180:183], v[16:19], v[116:119]
	ds_read_b128 v[250:253], v213 offset:17792
	s_waitcnt lgkmcnt(3)
	v_mfma_f32_16x16x32_bf16 v[120:123], v[236:239], v[16:19], v[120:123]
	ds_read_b128 v[180:183], v213 offset:52608
	s_waitcnt lgkmcnt(3)
	v_mfma_f32_16x16x32_bf16 v[116:119], v[240:243], v[20:23], v[116:119]
	ds_read_b128 v[236:239], v213 offset:17856
	s_waitcnt lgkmcnt(3)
	v_mfma_f32_16x16x32_bf16 v[120:123], v[244:247], v[20:23], v[120:123]
	ds_read_b128 v[240:243], v213 offset:52672
	s_waitcnt lgkmcnt(3)
	v_mfma_f32_16x16x32_bf16 v[116:119], v[250:253], v[24:27], v[116:119]
	ds_read_b128 v[244:247], v213 offset:26112
	s_waitcnt lgkmcnt(3)
	v_mfma_f32_16x16x32_bf16 v[120:123], v[180:183], v[24:27], v[120:123]
	ds_read_b128 v[250:253], v213 offset:60928
	s_waitcnt lgkmcnt(3)
	v_mfma_f32_16x16x32_bf16 v[116:119], v[236:239], v[28:31], v[116:119]
	ds_read_b128 v[180:183], v213 offset:26176
	s_waitcnt lgkmcnt(3)
	v_mfma_f32_16x16x32_bf16 v[120:123], v[240:243], v[28:31], v[120:123]
	ds_read_b128 v[236:239], v213 offset:60992
	s_waitcnt lgkmcnt(3)
	v_mfma_f32_16x16x32_bf16 v[124:127], v[244:247], v[0:3], 0
	ds_read_b128 v[240:243], v213 offset:26240
	s_waitcnt lgkmcnt(3)
	v_mfma_f32_16x16x32_bf16 v[128:131], v[250:253], v[0:3], 0
	ds_read_b128 v[244:247], v213 offset:61056
	s_waitcnt lgkmcnt(3)
	v_mfma_f32_16x16x32_bf16 v[124:127], v[180:183], v[4:7], v[124:127]
	ds_read_b128 v[250:253], v213 offset:26304
	s_waitcnt lgkmcnt(3)
	v_mfma_f32_16x16x32_bf16 v[128:131], v[236:239], v[4:7], v[128:131]
	ds_read_b128 v[180:183], v213 offset:61120
	s_waitcnt lgkmcnt(3)
	v_mfma_f32_16x16x32_bf16 v[124:127], v[240:243], v[8:11], v[124:127]
	ds_read_b128 v[236:239], v213 offset:26368
	s_waitcnt lgkmcnt(3)
	v_mfma_f32_16x16x32_bf16 v[128:131], v[244:247], v[8:11], v[128:131]
	ds_read_b128 v[240:243], v213 offset:61184
	s_waitcnt lgkmcnt(3)
	v_mfma_f32_16x16x32_bf16 v[124:127], v[250:253], v[12:15], v[124:127]
	ds_read_b128 v[244:247], v213 offset:26432
	s_waitcnt lgkmcnt(3)
	v_mfma_f32_16x16x32_bf16 v[128:131], v[180:183], v[12:15], v[128:131]
	ds_read_b128 v[250:253], v213 offset:61248
	s_waitcnt lgkmcnt(3)
	v_mfma_f32_16x16x32_bf16 v[124:127], v[236:239], v[16:19], v[124:127]
	ds_read_b128 v[180:183], v213 offset:26496
	s_waitcnt lgkmcnt(3)
	v_mfma_f32_16x16x32_bf16 v[128:131], v[240:243], v[16:19], v[128:131]
	ds_read_b128 v[236:239], v213 offset:61312
	s_waitcnt lgkmcnt(3)
	v_mfma_f32_16x16x32_bf16 v[124:127], v[244:247], v[20:23], v[124:127]
	ds_read_b128 v[170:173], v213 offset:26560
	s_waitcnt lgkmcnt(3)
	v_mfma_f32_16x16x32_bf16 v[128:131], v[250:253], v[20:23], v[128:131]
	ds_read_b128 v[174:177], v213 offset:61376
	s_waitcnt lgkmcnt(3)
	v_mfma_f32_16x16x32_bf16 v[124:127], v[180:183], v[24:27], v[124:127]
	s_waitcnt lgkmcnt(2)
	v_mfma_f32_16x16x32_bf16 v[128:131], v[236:239], v[24:27], v[128:131]
	s_waitcnt vmcnt(0)
	s_waitcnt vmcnt(0)
	s_waitcnt lgkmcnt(0)
	s_barrier
	global_load_lds_dwordx4 v[76:77], off
	v_lshl_add_u64 v[76:77], s[58:59], 0, v[148:149]
	s_mov_b32 m0, s48
	v_mfma_f32_16x16x32_bf16 v[124:127], v[170:173], v[28:31], v[124:127]
	global_load_lds_dwordx4 v[76:77], off
	v_lshl_add_u64 v[76:77], s[54:55], 0, v[150:151]
	s_mov_b32 m0, s49
	v_mfma_f32_16x16x32_bf16 v[128:131], v[174:177], v[28:31], v[128:131]
	global_load_lds_dwordx4 v[76:77], off
	v_lshl_add_u64 v[76:77], s[58:59], 0, v[150:151]
	s_mov_b32 m0, s62
	s_nop 0
	global_load_lds_dwordx4 v[76:77], off
	v_lshl_add_u64 v[76:77], s[54:55], 0, v[152:153]
	s_mov_b32 m0, s63
	s_nop 0
	global_load_lds_dwordx4 v[76:77], off
	v_lshl_add_u64 v[76:77], s[58:59], 0, v[152:153]
	s_mov_b32 m0, s64
	s_nop 0
	global_load_lds_dwordx4 v[76:77], off
	v_lshl_add_u64 v[76:77], s[54:55], 0, v[154:155]
	s_mov_b32 m0, s65
	s_nop 0
	global_load_lds_dwordx4 v[76:77], off
	v_lshl_add_u64 v[76:77], s[58:59], 0, v[154:155]
	s_mov_b32 m0, s66
	s_nop 0
	global_load_lds_dwordx4 v[76:77], off
	s_cbranch_vccnz .LBB0_1092
	s_mov_b32 m0, s82
	v_lshl_add_u64 v[170:171], s[54:55], 0, v[156:157]
	v_lshl_add_u64 v[76:77], s[58:59], 0, v[156:157]
	global_load_lds_dwordx4 v[170:171], off
	s_add_i32 m0, s82, 0x8800
	s_nop 0
	global_load_lds_dwordx4 v[76:77], off
